# XU: cross-unit prefetch of the next attention unit's first K/V tiles by the idle waves 4-7 (alt LDS + copy) on top of S2+peel+XL
# baseline (speedup 1.0000x reference)
.Lxu_w47:
	s_cmp_eq_u32 s64, 32
	s_cbranch_scc0 .LBB0_266
	s_cmp_lt_u32 s60, 3
	s_cbranch_scc0 .LBB0_266
	s_add_u32 s0, s28, 0x800000
	s_mov_b32 s1, 0
	s_sub_u32 s14, s0, 0x10000
	s_subb_u32 s15, s1, 0
	s_add_i32 m0, s70, 0x14000
	v_lshl_add_u64 v[66:67], v[188:189], 0, s[0:1]
	global_load_lds_dwordx4 v[66:67], off
	s_add_i32 m0, s70, 0x14400
	v_lshl_add_u64 v[66:67], v[192:193], 0, s[0:1]
	global_load_lds_dwordx4 v[66:67], off
	s_add_i32 m0, s70, 0x12000
	v_lshl_add_u64 v[66:67], v[188:189], 0, s[14:15]
	global_load_lds_dwordx4 v[66:67], off
	s_add_i32 m0, s70, 0x12400
	v_lshl_add_u64 v[66:67], v[192:193], 0, s[14:15]
	global_load_lds_dwordx4 v[66:67], off
	s_lshl_b32 s0, s34, 1
	s_add_u32 s0, s0, 0x2000
	s_mov_b32 s1, 0
	s_sub_u32 s14, s0, 0x200000
	s_subb_u32 s15, s1, 0
	s_add_i32 m0, s70, 0x18000
	v_lshl_add_u64 v[66:67], v[190:191], 0, s[0:1]
	global_load_lds_dwordx4 v[66:67], off
	s_add_i32 m0, s70, 0x18400
	v_lshl_add_u64 v[66:67], v[194:195], 0, s[0:1]
	global_load_lds_dwordx4 v[66:67], off
	s_add_i32 m0, s70, 0x16000
	v_lshl_add_u64 v[66:67], v[190:191], 0, s[14:15]
	global_load_lds_dwordx4 v[66:67], off
	s_add_i32 m0, s70, 0x16400
	v_lshl_add_u64 v[66:67], v[194:195], 0, s[14:15]
	global_load_lds_dwordx4 v[66:67], off
	s_add_u32 s0, s30, 0x800000
	s_mov_b32 s1, 0
	s_sub_u32 s14, s0, 0x10000
	s_subb_u32 s15, s1, 0
	s_add_i32 m0, s70, 0x1c000
	v_lshl_add_u64 v[66:67], v[188:189], 0, s[0:1]
	global_load_lds_dwordx4 v[66:67], off
	s_add_i32 m0, s70, 0x1c400
	v_lshl_add_u64 v[66:67], v[192:193], 0, s[0:1]
	global_load_lds_dwordx4 v[66:67], off
	s_add_i32 m0, s70, 0x1a000
	v_lshl_add_u64 v[66:67], v[188:189], 0, s[14:15]
	global_load_lds_dwordx4 v[66:67], off
	s_add_i32 m0, s70, 0x1a400
	v_lshl_add_u64 v[66:67], v[192:193], 0, s[14:15]
	global_load_lds_dwordx4 v[66:67], off

.LBB0_275:
	s_or_b64 exec, exec, s[0:1]
	s_ashr_i32 s69, s63, 6
	s_and_b32 s27, s69, 3
	s_lshl_b32 s14, s62, 7
	s_add_i32 s0, s14, s61
	s_lshl_b32 s15, s27, 5
	v_and_b32_e32 v199, 31, v10
	s_or_b32 s0, s15, s0
	v_or_b32_e32 v12, s0, v199
	s_ashr_i32 s26, s63, 8
	v_ashrrev_i32_e32 v13, 31, v12
	v_lshlrev_b64 v[2:3], 11, v[12:13]
	s_lshl_b32 s0, s26, 6
	v_bfe_u32 v198, v10, 5, 1
	v_lshl_add_u64 v[2:3], s[44:45], 0, v[2:3]
	s_ashr_i32 s1, s0, 31
	v_lshl_add_u64 v[2:3], s[0:1], 1, v[2:3]
	v_lshlrev_b32_e32 v0, 4, v198
	v_bfe_u32 v4, v10, 4, 2
	s_lshl_b32 s1, s69, 3
	v_lshl_add_u64 v[2:3], v[2:3], 0, v[0:1]
	v_or_b32_e32 v0, s1, v4
	global_load_dword v200, v1, s[4:5] offset:256
	global_load_dword v201, v1, s[4:5] offset:2812
	global_load_dwordx4 v[130:133], v[2:3], off
	global_load_dwordx4 v[134:137], v[2:3], off offset:32
	global_load_dwordx4 v[138:141], v[2:3], off offset:64
	global_load_dwordx4 v[142:145], v[2:3], off offset:96
	v_add_u32_e32 v2, s61, v0
	v_bitop3_b32 v6, s1, v10, v4 bitop3:0x36
	v_ashrrev_i32_e32 v3, 31, v2
	v_lshlrev_b64 v[2:3], 11, v[2:3]
	v_lshlrev_b32_e32 v0, 4, v6
	v_bfe_u32 v5, v10, 3, 3
	v_lshl_add_u64 v[2:3], s[46:47], 0, v[2:3]
	v_and_b32_e32 v0, 0xf0, v0
	v_lshl_add_u64 v[188:189], v[2:3], 0, v[0:1]
	v_or_b32_e32 v2, s67, v5
	v_lshl_add_u32 v2, s69, 4, v2
	s_lshl_b32 s0, s69, 1
	v_xor_b32_e32 v0, v4, v10
	v_ashrrev_i32_e32 v3, 31, v2
	v_lshlrev_b64 v[2:3], 15, v[2:3]
	v_lshlrev_b32_e32 v0, 4, v0
	s_or_b32 s0, s0, 1
	v_lshl_add_u64 v[2:3], s[50:51], 0, v[2:3]
	v_and_b32_e32 v0, 0x70, v0
	s_lshl_b32 s1, s0, 2
	v_lshl_add_u64 v[190:191], v[2:3], 0, v[0:1]
	v_or_b32_e32 v0, s1, v4
	v_add_u32_e32 v2, s61, v0
	v_bitop3_b32 v4, s1, v10, v4 bitop3:0x36
	v_ashrrev_i32_e32 v3, 31, v2
	v_lshlrev_b64 v[2:3], 11, v[2:3]
	v_lshlrev_b32_e32 v0, 4, v4
	v_lshl_add_u64 v[2:3], s[46:47], 0, v[2:3]
	v_and_b32_e32 v0, 0xf0, v0
	v_lshl_add_u64 v[192:193], v[2:3], 0, v[0:1]
	v_lshl_or_b32 v0, s0, 3, v5
	v_lshrrev_b32_e32 v2, 1, v0
	v_xor_b32_e32 v4, v2, v10
	v_add_u32_e32 v2, s67, v0
	v_ashrrev_i32_e32 v3, 31, v2
	v_lshlrev_b64 v[2:3], 15, v[2:3]
	v_lshlrev_b32_e32 v0, 4, v4
	s_lshl_b32 s0, s69, 11
	v_lshl_add_u64 v[2:3], s[50:51], 0, v[2:3]
	v_and_b32_e32 v0, 0x70, v0
	s_add_i32 s70, s0, 0
	s_mov_b32 s29, s23
	v_lshl_add_u64 v[194:195], v[2:3], 0, v[0:1]
	s_mov_b64 vcc, 0
	s_cmp_eq_u32 s64, 32
	s_cbranch_scc0 .Lxu_pf0
	s_cmp_eq_u32 s60, 0
	s_cbranch_scc1 .Lxu_pf0
	s_mov_b64 vcc, -1
.Lxu_pf0:
	v_lshl_add_u64 v[2:3], v[188:189], 0, s[28:29]
	s_mov_b32 m0, s70
	s_add_i32 s71, s70, 0x8000
	s_cbranch_vccnz .Lxu_s0
	global_load_lds_dwordx4 v[2:3], off
.Lxu_s0:
	v_lshl_add_u64 v[2:3], v[192:193], 0, s[28:29]
	s_add_i32 s29, s70, 0x400
	s_mov_b32 m0, s29
	s_lshl_b64 s[0:1], s[34:35], 1
	s_cbranch_vccnz .Lxu_s1
	global_load_lds_dwordx4 v[2:3], off
.Lxu_s1:
	v_lshl_add_u64 v[2:3], v[190:191], 0, s[0:1]
	s_mov_b32 m0, s71
	s_add_i32 s72, s70, 0x8400
	s_cbranch_vccnz .Lxu_s2
	global_load_lds_dwordx4 v[2:3], off
.Lxu_s2:
	v_lshl_add_u64 v[2:3], v[194:195], 0, s[0:1]
	s_mov_b32 m0, s72
	s_add_i32 s73, s70, 0x4000
	s_mov_b32 s31, s23
	s_cbranch_vccnz .Lxu_s3
	global_load_lds_dwordx4 v[2:3], off
.Lxu_s3:
	v_lshl_add_u64 v[2:3], v[188:189], 0, s[30:31]
	s_mov_b32 m0, s73
	v_and_b32_e32 v0, 19, v10
	s_cbranch_vccnz .Lxu_s4
	global_load_lds_dwordx4 v[2:3], off
.Lxu_s4:
	v_lshl_add_u64 v[2:3], v[192:193], 0, s[30:31]
	s_add_i32 s31, s70, 0x4400
	s_mov_b32 m0, s31
	v_lshrrev_b32_e32 v11, 1, v10
	s_cbranch_vccnz .Lxu_s5
	global_load_lds_dwordx4 v[2:3], off
.Lxu_s5:
	v_lshlrev_b32_e32 v2, 1, v10
	v_and_or_b32 v17, v2, 8, v0
	v_and_b32_e32 v18, 4, v11
	v_or_b32_e32 v2, v17, v18
	v_lshl_or_b32 v14, s26, 3, v198
	v_lshlrev_b32_e32 v0, 8, v2
	v_bitop3_b32 v2, v2, v14, 15 bitop3:0x6c
	s_or_b32 s14, s15, s14
	v_lshl_add_u32 v2, v2, 4, v0
	s_add_i32 s74, s14, 0xffffffa5
	v_add_u32_e32 v202, 0, v2
	s_cmp_gt_i32 s65, s74
	s_waitcnt vmcnt(0)
	s_waitcnt vmcnt(0) lgkmcnt(0)
	s_barrier
	s_cbranch_vccz .Lxu_nocopy
	v_and_b32_e32 v66, 63, v10
	v_lshlrev_b32_e32 v66, 4, v66
	v_add_u32_e32 v66, s70, v66
	v_add_u32_e32 v67, 0x14000, v66
	ds_read_b128 v[68:71], v67
	ds_read_b128 v[72:75], v67 offset:1024
	ds_read_b128 v[76:79], v67 offset:16384
	ds_read_b128 v[80:83], v67 offset:17408
	ds_read_b128 v[84:87], v67 offset:32768
	ds_read_b128 v[88:91], v67 offset:33792
	s_waitcnt lgkmcnt(0)
	ds_write_b128 v66, v[68:71]
	ds_write_b128 v66, v[72:75] offset:1024
	ds_write_b128 v66, v[76:79] offset:32768
	ds_write_b128 v66, v[80:83] offset:33792
	ds_write_b128 v66, v[84:87] offset:16384
	ds_write_b128 v66, v[88:91] offset:17408
	s_waitcnt lgkmcnt(0)
	s_barrier
.Lxu_nocopy:
	s_cmp_gt_i32 s65, s74
	ds_read_b128 v[6:9], v202
	ds_read_b128 v[2:5], v202 offset:8192
	s_cselect_b64 s[0:1], -1, 0
	s_add_i32 s75, s14, 0x7a
	s_cmp_lt_i32 s34, s75
	s_cselect_b64 s[40:41], -1, 0
	s_and_b64 s[0:1], s[0:1], s[40:41]
	s_andn2_b64 vcc, exec, s[0:1]
	s_mov_b64 s[0:1], -1
	s_cbranch_vccz .LBB0_277
	s_waitcnt lgkmcnt(1)
	v_mfma_f32_32x32x16_bf16 v[66:81], v[6:9], v[130:133], 0
	s_mov_b64 s[0:1], 0
	s_waitcnt lgkmcnt(0)
	v_mfma_f32_32x32x16_bf16 v[82:97], v[2:5], v[130:133], 0
